# attention work queue: next item index fetched (atomic) one item ahead
# baseline (speedup 1.0000x reference)
; DI int TIDX() { int t = (int)threadIdx.x; asm volatile("" : "+v"(t)); return t; }
; DI void phase_d(const Params& p, int layer, unsigned char* smem) {
;   unsigned* qctr = (unsigned*)(p.ws + O_BAR) + 130 + layer;
;   int* s_it = (int*)(smem + SMEM_BYTES - 16);
;   for (;;) {
;     if (TIDX() == 0) *s_it = (int)atomicAdd(qctr, 1u);
;     __syncthreads();
;     const int it = *s_it;
;     __syncthreads();
.LBB0_585:
	s_or_b64 exec, exec, s[0:1]
	v_readlane_b32 s0, v241, 0
	v_readlane_b32 s1, v241, 1
	s_add_u32 s2, s0, 0x9554000
	s_addc_u32 s3, s1, 0
	v_writelane_b32 v237, s2, 13
	v_mbcnt_hi_u32_b32 v221, -1, v184
	s_movk_i32 s70, 0xff80
	v_writelane_b32 v237, s3, 14
	s_add_u32 s2, s0, 0x4b54000
	s_addc_u32 s3, s1, 0
	v_writelane_b32 v240, s2, 26
	s_waitcnt lgkmcnt(0)
	v_and_b32_e32 v0, 64, v221
	s_mov_b32 s69, 0
	v_writelane_b32 v240, s3, 27
	s_add_u32 s2, s0, 0x1df54000
	s_addc_u32 s3, s1, 0
	v_writelane_b32 v240, s2, 35
	v_mov_b32_e32 v1, 0
	v_mov_b32_e32 v174, 0x23ff0
	v_writelane_b32 v240, s3, 36
	s_add_u32 s2, s0, 0xcd54000
	v_writelane_b32 v237, s2, 15
	s_addc_u32 s2, s1, 0
	v_writelane_b32 v237, s2, 16
	s_add_u32 s2, s0, 0xdd54000
	v_writelane_b32 v237, s2, 17
	s_addc_u32 s2, s1, 0
	v_writelane_b32 v237, s2, 18
	s_add_u32 s2, s0, 0x1e554000
	v_writelane_b32 v240, s2, 28
	s_addc_u32 s2, s1, 0
	v_writelane_b32 v240, s2, 29
	s_add_u32 s2, s0, 0xc554000
	v_writelane_b32 v237, s2, 19
	s_addc_u32 s2, s1, 0
	v_writelane_b32 v237, s2, 20
	s_add_u32 s2, s0, 0xd554000
	v_writelane_b32 v237, s2, 21
	s_addc_u32 s2, s1, 0
	v_writelane_b32 v237, s2, 22
	s_add_u32 s2, s0, 0x1b754000
	s_addc_u32 s3, s1, 0
	v_writelane_b32 v240, s2, 23
	s_mov_b32 s84, 0x2aaaaaab
	s_movk_i32 s85, 0x200
	v_writelane_b32 v240, s3, 24
	s_add_u32 s2, s0, 0xe554000
	s_addc_u32 s3, s1, 0
	v_writelane_b32 v240, s2, 30
	s_movk_i32 s86, 0x48
	s_movk_i32 s87, 0x220
	v_writelane_b32 v240, s3, 31
	s_add_u32 s2, s0, 0x10554000
	s_addc_u32 s3, s1, 0
	v_writelane_b32 v237, s2, 23
	s_mov_b32 s88, 0x41800000
	s_movk_i32 s90, 0x600
	v_writelane_b32 v237, s3, 24
	s_add_u32 s2, s0, 0x1e354000
	v_writelane_b32 v237, s2, 25
	s_addc_u32 s2, s1, 0
	v_writelane_b32 v237, s2, 26
	s_add_u32 s2, s0, 0x12554000
	v_writelane_b32 v237, s2, 27
	s_addc_u32 s2, s1, 0
	v_writelane_b32 v237, s2, 28
	s_add_u32 s2, s0, 0x14554000
	s_addc_u32 s3, s1, 0
	v_writelane_b32 v240, s2, 14
	s_mov_b32 s71, -1
	s_movk_i32 s92, 0x68
	v_writelane_b32 v240, s3, 15
	s_add_u32 s2, s0, 0x17554000
	s_addc_u32 s3, s1, 0
	v_writelane_b32 v237, s2, 29
	v_xor_b32_e32 v222, 32, v221
	v_add_u32_e32 v223, 64, v0
	v_writelane_b32 v237, s3, 30
	s_add_u32 s2, s0, 0x1b554000
	s_addc_u32 s3, s1, 0
	s_add_u32 s0, s0, 0x19554000
	s_addc_u32 s1, s1, 0
	v_writelane_b32 v240, s2, 32
	v_writelane_b32 v237, s0, 31
	v_mov_b32_e32 v175, 0xff800000
	s_barrier
	v_writelane_b32 v240, s3, 33
	v_writelane_b32 v237, s1, 32
	s_mov_b32 s99, 0
	s_branch .LBB0_590

; DI int TIDX() { int t = (int)threadIdx.x; asm volatile("" : "+v"(t)); return t; }
; DI void phase_d(const Params& p, int layer, unsigned char* smem) {
;     ...
;   for (;;) {
;     if (TIDX() == 0) *s_it = (int)atomicAdd(qctr, 1u);
;     __syncthreads();
;     const int it = *s_it;
;     __syncthreads();
.LBB0_590:
	v_mov_b32_e32 v0, v220
	s_nop 0
	v_cmp_eq_u32_e32 vcc, 0, v0
	s_and_saveexec_b64 s[0:1], vcc
	s_cbranch_execz .LBB0_594
	s_mov_b64 s[4:5], exec
	v_mbcnt_lo_u32_b32 v0, s4, 0
	v_mbcnt_hi_u32_b32 v0, s5, v0
	v_cmp_eq_u32_e32 vcc, 0, v0
	s_and_saveexec_b64 s[2:3], vcc
	s_cbranch_execz .LBB0_593
	s_bcnt1_i32_b64 s4, s[4:5]
	v_mov_b32_e32 v2, s4
	v_readlane_b32 s4, v241, 0
	v_readlane_b32 s5, v241, 1
	s_nop 4
	s_cmp_lg_u32 s99, 0
	s_cbranch_scc1 .Lqa_have
	global_atomic_add v238, v1, v2, s[4:5] offset:520 sc0
.Lqa_have:
	s_waitcnt vmcnt(0)
	v_mov_b32_e32 v239, v238
	global_atomic_add v238, v1, v2, s[4:5] offset:520 sc0
	s_mov_b32 s99, 1
	v_mov_b32_e32 v2, v239
.LBB0_593:
	s_or_b64 exec, exec, s[2:3]
	v_readfirstlane_b32 s2, v2
	s_nop 1
	v_add_u32_e32 v0, s2, v0
	ds_write_b32 v174, v0

; DI int TIDX() { int t = (int)threadIdx.x; asm volatile("" : "+v"(t)); return t; }
; DI void phase_d(const Params& p, int layer, unsigned char* smem) {
;   unsigned* qctr = (unsigned*)(p.ws + O_BAR) + 130 + layer;
;   int* s_it = (int*)(smem + SMEM_BYTES - 16);
;   for (;;) {
;     if (TIDX() == 0) *s_it = (int)atomicAdd(qctr, 1u);
.LBB0_1619:
	s_or_b64 exec, exec, s[0:1]
	s_movk_i32 s70, 0xff80
	s_mov_b32 s69, 0
	v_mov_b32_e32 v1, 0
	v_mov_b32_e32 v174, 0x23ff0
	s_mov_b32 s84, 0x2aaaaaab
	s_movk_i32 s85, 0x200
	s_movk_i32 s86, 0x48
	s_movk_i32 s87, 0x220
	s_mov_b32 s88, 0x41800000
	s_movk_i32 s90, 0x600
	s_mov_b32 s71, -1
	s_movk_i32 s92, 0x68
	v_mov_b32_e32 v175, 0xff800000
	s_waitcnt lgkmcnt(0)
	s_barrier
	s_mov_b32 s99, 0
	s_branch .LBB0_1624

; DI int TIDX() { int t = (int)threadIdx.x; asm volatile("" : "+v"(t)); return t; }
; DI void phase_d(const Params& p, int layer, unsigned char* smem) {
;     ...
;     if (TIDX() == 0) *s_it = (int)atomicAdd(qctr, 1u);
;     __syncthreads();
;     const int it = *s_it;
;     __syncthreads();
.LBB0_1624:
	v_mov_b32_e32 v0, v220
	s_nop 0
	v_cmp_eq_u32_e32 vcc, 0, v0
	s_and_saveexec_b64 s[0:1], vcc
	s_cbranch_execz .LBB0_1628
	s_mov_b64 s[4:5], exec
	v_mbcnt_lo_u32_b32 v0, s4, 0
	v_mbcnt_hi_u32_b32 v0, s5, v0
	v_cmp_eq_u32_e32 vcc, 0, v0
	s_and_saveexec_b64 s[2:3], vcc
	s_cbranch_execz .LBB0_1627
	s_bcnt1_i32_b64 s4, s[4:5]
	v_mov_b32_e32 v2, s4
	v_readlane_b32 s4, v241, 0
	v_readlane_b32 s5, v241, 1
	s_nop 4
	s_cmp_lg_u32 s99, 0
	s_cbranch_scc1 .Lqb_have
	global_atomic_add v238, v1, v2, s[4:5] offset:524 sc0
.Lqb_have:
	s_waitcnt vmcnt(0)
	v_mov_b32_e32 v239, v238
	global_atomic_add v238, v1, v2, s[4:5] offset:524 sc0
	s_mov_b32 s99, 1
	v_mov_b32_e32 v2, v239
